# SwiGLU activations relocated (no longer alias other token tiles' P rows): the cross-out -> FFN2-up seam also uses the XCD-local barrier (5 of 12 seams per layer)
# baseline (speedup 1.0000x reference)
; #define PG8_STAGE(bufoff, gbase, voff) do { _Pragma("unroll") for (int _i = 0; _i < 2; ++_i) \
;         __builtin_amdgcn_global_load_lds((const unsigned*)((const char*)(gbase) + (voff)[_i]), (PG8_LAS unsigned*)(lds + (bufoff) + ldsw + _i * 8192), 16, 0, 0); } while (0)
; #define PG8_WAIT_V(n) asm volatile("s_waitcnt vmcnt(" #n ")" ::: "memory")
; #define PG8_BAR __builtin_amdgcn_s_barrier()
; template <class Epi, class Sched, bool ALIGN_EPI = false, bool SP2 = false>
; __device__ __forceinline__ void gemm_phase(PG8_LAS unsigned char* lds, const Gemm g, const Sched& S, const Epi& E) {
;     ...
;         PG8_STAGE(PG8_SB(0, 0), cB, voffB); PG8_STAGE(PG8_SB(0, 1), cB + hstepB, voffB); PG8_STAGE(PG8_SA(0, 0), cA, voffA); PG8_STAGE(PG8_SA(0, 1), cA + hstepA, voffA);
;         if (wr == 1) PG8_BAR;
;         PG8_WAIT_V(2); PG8_BAR;
;         PG8_STAGE(PG8_SB(1, 0), cB + kstep, voffB); PG8_STAGE(PG8_SA(1, 0), cA + kstep, voffA); PG8_STAGE(PG8_SB(1, 1), cB + hstepB + kstep, voffB);
;         PG8_WAIT_V(6); PG8_BAR;
; __global__ void __launch_bounds__(NTHREADS, 2) mega_fwd(Args args) {
;     ...
;             pg8::Gemm g{XB, (const bf16*)(ws + WS_W1A), M, 2 * FFH, DM, DM, DM}; pg8::StaticOrder S; S.init(M, 2 * FFH, G_, bx_);
;             EpiSwiglu E{ACT, SSQ};
;             pg8::gemm_phase<EpiSwiglu, pg8::StaticOrder, true, true>(ldsp, g, S, E);
.LBB0_150:
	s_add_u32 s12, s6, 0x7a00000
	s_addc_u32 s13, s7, 0
	s_lshl_b32 s8, s15, 5
	s_add_i32 s49, s1, 0x18000
	s_and_b32 s17, s8, 0x60
	s_add_i32 s50, s49, s2
	s_lshl_b32 s16, s14, 13
	s_lshl_b32 s15, s17, 7
	v_lshl_add_u64 v[6:7], v[6:7], 0, s[76:77]
	s_mov_b32 m0, s50
	s_add_i32 s51, s50, 0x2000
	s_add_i32 s60, s43, 0x8000
	s_add_i32 s61, s43, 0xa000
	s_waitcnt vmcnt(2)
	s_barrier
	global_load_lds_dwordx4 v[6:7], off
	v_lshl_add_u64 v[4:5], v[4:5], 0, s[76:77]
	s_mov_b32 m0, s51
	s_add_u32 s8, s26, 0x40080
	global_load_lds_dwordx4 v[4:5], off
	v_lshl_add_u64 v[0:1], v[0:1], 0, s[76:77]
	s_mov_b32 m0, s60
	s_addc_u32 s9, s27, 0
	s_add_i32 s64, s1, 0x1c000
	global_load_lds_dwordx4 v[0:1], off
	v_lshl_add_u64 v[0:1], v[2:3], 0, s[76:77]
	s_mov_b32 m0, s61
	s_add_i32 s65, s64, s2
	global_load_lds_dwordx4 v[0:1], off
	v_lshl_add_u64 v[0:1], s[8:9], 0, v[192:193]
	s_mov_b32 m0, s65
	s_add_i32 s66, s65, 0x2000
	global_load_lds_dwordx4 v[0:1], off
	v_lshl_add_u64 v[0:1], s[8:9], 0, v[128:129]
	s_mov_b32 m0, s66
	v_bfe_u32 v2, v9, 4, 2
	global_load_lds_dwordx4 v[0:1], off
	v_and_b32_e32 v1, 15, v9
	v_lshlrev_b32_e32 v0, 4, v2
	v_lshlrev_b32_e32 v3, 2, v9
	v_lshl_or_b32 v148, s14, 6, v1
	v_lshl_or_b32 v1, v1, 6, v0
	v_and_b32_e32 v3, 32, v3
	v_bitop3_b32 v4, v1, s16, v3 bitop3:0xde
	v_bitop3_b32 v149, v1, s15, v3 bitop3:0xde
	v_mov_b32_e32 v1, v193
	s_sext_i32_i16 s70, s4
	s_cmpk_lt_u32 s5, 0x100
	v_lshl_add_u64 v[0:1], s[6:7], 0, v[0:1]
	s_mov_b64 s[4:5], 0x3600000
	v_lshl_add_u64 v[134:135], v[0:1], 0, s[4:5]
	v_lshlrev_b32_e32 v0, 14, v8
	v_and_b32_e32 v0, 0xffff8000, v0
	v_lshl_add_u32 v0, v10, 11, v0
	v_and_b32_e32 v1, 1, v8
	v_lshl_or_b32 v0, v1, 6, v0
	v_lshl_add_u32 v136, v11, 1, v0
	v_lshlrev_b32_e32 v0, 14, v13
	v_and_b32_e32 v0, 0xffff8000, v0
	s_waitcnt vmcnt(6)
	v_lshl_add_u32 v0, v12, 11, v0
	v_and_b32_e32 v1, 1, v13
	v_lshl_or_b32 v0, v1, 6, v0
	s_cselect_b64 s[14:15], -1, 0
	s_ashr_i32 s67, s0, 31
	v_lshl_or_b32 v150, v2, 3, s17
	v_mov_b32_e32 v137, v193
	v_lshl_add_u32 v138, v14, 1, v0
	v_mov_b32_e32 v139, v193
	s_mov_b32 s68, 0
	v_add_u32_e32 v151, s1, v4
	s_barrier
	s_branch .LBB0_153

; template <class Epi, class Sched, bool ALIGN_EPI = false, bool SP2 = false>
; __device__ __forceinline__ void gemm_phase(PG8_LAS unsigned char* lds, const Gemm g, const Sched& S, const Epi& E) {
;     ...
;     for (int i = 0; i < 2; ++i) { int R, C; stage_rc(tid * 16 + i * 8192, R, C); const int Rb = Epi::PERM ? ((R & ~31) + perm32(R & 31)) : R;
;         voffA[i] = (unsigned)(R * g.lda + C) * 2u; voffB[i] = (unsigned)(Rb * g.ldb + C) * 2u; }
;     const size_t kstep = (size_t)(BK * 2);
;     const size_t hstepA = (size_t)HALF * g.lda * 2, hstepB = (size_t)HALF * g.ldb * 2;
; __global__ void __launch_bounds__(NTHREADS, 2) mega_fwd(Args args) {
;     ...
;             pg8::Gemm g{ACT, (const bf16*)(ws + WS_W1B), M, DM, FFH, FFH, FFH}; pg8::StaticOrder S; S.init(M, DM, G_, bx_);
;             EpiRes E{XB, SSQ, 0.5f};
;             pg8::gemm_phase<EpiRes, pg8::StaticOrder, true, true>(ldsp, g, S, E);
.LBB0_261:
	v_readlane_b32 s8, v255, 31
	v_readlane_b32 s9, v255, 32
	s_xor_b64 s[8:9], s[8:9], -1
	v_writelane_b32 v255, s8, 33
	s_andn2_b64 vcc, exec, s[6:7]
	s_nop 0
	v_writelane_b32 v255, s9, 34
	s_cbranch_vccnz .LBB0_301
	v_ashrrev_i32_e32 v1, 31, v12
	v_lshrrev_b32_e32 v1, 26, v1
	v_add_u32_e32 v1, v12, v1
	v_ashrrev_i32_e32 v8, 6, v1
	v_bfe_i32 v1, v12, 27, 1
	v_lshlrev_b32_e32 v0, 4, v12
	v_lshrrev_b32_e32 v1, 22, v1
	v_add_u32_e32 v1, v0, v1
	v_and_b32_e32 v1, 0xfffffc00, v1
	v_sub_u32_e32 v1, v0, v1
	v_lshrrev_b32_e32 v2, 4, v1
	v_bitop3_b32 v1, v2, v1, 32 bitop3:0x6c
	v_ashrrev_i32_e32 v3, 31, v1
	v_lshrrev_b32_e32 v3, 26, v3
	v_lshlrev_b32_e32 v2, 3, v8
	v_add_u32_e32 v3, v1, v3
	v_and_b32_e32 v2, -16, v2
	v_ashrrev_i32_e32 v10, 6, v3
	v_and_b32_e32 v3, 0xc0, v3
	v_add_u32_e32 v2, v10, v2
	v_lshlrev_b32_e32 v4, 5, v8
	v_sub_u32_e32 v1, v1, v3
	v_and_b32_e32 v9, 32, v4
	v_ashrrev_i16_sdwa v1, v244, sext(v1) dst_sel:DWORD dst_unused:UNUSED_PAD src0_sel:DWORD src1_sel:BYTE_0
	v_lshlrev_b32_e32 v3, 1, v2
	v_lshrrev_b32_e32 v4, 2, v2
	v_and_b32_e32 v5, 3, v10
	s_mov_b32 s7, 0xffffe0
	v_bfe_i32 v11, v1, 0, 16
	v_and_b32_e32 v3, 24, v3
	v_and_b32_e32 v4, 4, v4
	v_and_or_b32 v5, v2, s7, v5
	s_movk_i32 s2, 0xb00
	v_add_u32_e32 v1, v9, v11
	v_or3_b32 v3, v5, v4, v3
	v_mul_lo_u32 v2, v2, s2
	v_add_lshl_u32 v128, v1, v2, 1
	v_mul_u32_u24_e32 v2, 0xb00, v3
	v_add_u32_e32 v0, 0x2000, v0
	v_add_lshl_u32 v192, v2, v1, 1
	v_ashrrev_i32_e32 v1, 31, v0
	v_lshrrev_b32_e32 v1, 22, v1
	v_add_u32_e32 v1, v0, v1
	v_ashrrev_i32_e32 v13, 10, v1
	v_mul_i32_i24_e32 v1, 0x400, v13
	v_sub_u32_e32 v0, v0, v1
	v_lshrrev_b32_e32 v1, 4, v0
	v_bitop3_b32 v0, v1, v0, 32 bitop3:0x6c
	v_ashrrev_i32_e32 v2, 31, v0
	s_add_u32 s28, s4, 0x7a00000
	v_lshrrev_b32_e32 v2, 26, v2
	s_addc_u32 s29, s5, 0
	v_lshlrev_b32_e32 v1, 3, v13
	v_add_u32_e32 v2, v0, v2
	s_add_u32 s30, s4, 0xb00000
	v_and_b32_e32 v1, -16, v1
	v_ashrrev_i32_e32 v15, 6, v2
	s_addc_u32 s31, s5, 0
	s_ashr_i32 s6, s16, 6
	v_add_u32_e32 v1, v15, v1
	v_lshlrev_b32_e32 v3, 5, v13
	v_and_b32_e32 v2, 0xc0, v2
	v_and_b32_e32 v4, 3, v15
	v_and_b32_e32 v14, 32, v3
	v_sub_u32_e32 v0, v0, v2
	v_lshlrev_b32_e32 v2, 1, v1
	v_lshrrev_b32_e32 v3, 2, v1
	v_and_or_b32 v4, v1, s7, v4
	v_mul_lo_u32 v1, v1, s2
	s_ashr_i32 s7, s16, 8
	s_lshl_b32 s2, s6, 10
	s_mul_i32 s9, s34, 0x160000
	s_mul_hi_i32 s8, s34, 0x160000
	s_add_u32 s22, s30, s9
	s_addc_u32 s23, s31, s8
	s_add_i32 s35, s18, 0x10000
	s_add_i32 s36, s35, s2
	s_add_i32 s37, s36, 0x2000
	v_ashrrev_i16_sdwa v0, v244, sext(v0) dst_sel:DWORD dst_unused:UNUSED_PAD src0_sel:DWORD src1_sel:BYTE_0
	s_add_u32 s8, s22, 0xb0000
	v_bfe_i32 v16, v0, 0, 16
	v_and_b32_e32 v2, 24, v2
	v_and_b32_e32 v3, 4, v3
	s_addc_u32 s9, s23, 0
	s_add_i32 s38, s18, 0x14000
	v_add_u32_e32 v0, v14, v16
	v_or3_b32 v2, v4, v3, v2
	s_add_i32 s39, s38, s2
	v_add_lshl_u32 v130, v0, v1, 1
	v_mul_u32_u24_e32 v1, 0xb00, v2
	s_mul_i32 s11, s68, 0x160000
	s_mov_b32 m0, s36
	s_add_i32 s40, s39, 0x2000
	v_add_lshl_u32 v132, v1, v0, 1
	s_mul_hi_i32 s10, s68, 0x160000
	global_load_lds_dwordx4 v192, s[22:23]
	s_mov_b32 m0, s37
	s_add_u32 s20, s28, s11
	global_load_lds_dwordx4 v132, s[22:23]
	s_mov_b32 m0, s39
	s_addc_u32 s21, s29, s10
	s_add_i32 s41, s18, s2
	global_load_lds_dwordx4 v192, s[8:9]
	s_mov_b32 m0, s40
	s_add_i32 s42, s41, 0x2000
	global_load_lds_dwordx4 v132, s[8:9]
	s_mov_b32 m0, s41
	s_add_u32 s8, s20, 0xb0000
	global_load_lds_dwordx4 v128, s[20:21]
	s_mov_b32 m0, s42
	s_addc_u32 s9, s21, 0
	s_add_i32 s43, s41, 0x4000
	global_load_lds_dwordx4 v130, s[20:21]
	s_mov_b32 m0, s43
	s_add_i32 s44, s41, 0x6000
	global_load_lds_dwordx4 v128, s[8:9]
	s_mov_b32 m0, s44
	v_mov_b32_e32 v133, v193
	global_load_lds_dwordx4 v130, s[8:9]
	v_mov_b32_e32 v129, v193
	v_mov_b32_e32 v131, v193
	s_cmp_eq_u32 s7, 1
	v_lshl_add_u64 v[6:7], s[22:23], 0, v[192:193]
	v_lshl_add_u64 v[4:5], s[22:23], 0, v[132:133]
	v_lshl_add_u64 v[0:1], s[20:21], 0, v[128:129]
	s_cselect_b64 s[10:11], -1, 0
	s_cmp_lg_u32 s7, 1
	v_lshl_add_u64 v[2:3], s[20:21], 0, v[130:131]
	s_cbranch_scc1 .LBB0_264
	s_barrier

; __global__ void __launch_bounds__(NTHREADS, 2) mega_fwd(Args args) {
;     ...
;         {   PHASE_PTRS
;             pg8::Gemm g{XB, (const bf16*)(ws + WS_W2A), M, 2 * FFH, DM, DM, DM}; pg8::StaticOrder S; S.init(M, 2 * FFH, G_, bx_);
;             EpiSwiglu E{ACT, SSQ};
;             pg8::gemm_phase<EpiSwiglu, pg8::StaticOrder, true, true>(ldsp, g, S, E);
.LBB0_1215:
	v_bfe_u32 v18, v14, 4, 2
	s_sext_i32_i16 s66, s8
	s_add_u32 s8, s4, 0x7a00000
	v_and_b32_e32 v15, 15, v14
	v_lshlrev_b32_e32 v16, 4, v18
	v_lshlrev_b32_e32 v14, 2, v14
	s_addc_u32 s9, s5, 0
	v_lshl_or_b32 v148, s2, 6, v15
	v_lshl_or_b32 v15, v15, 6, v16
	s_lshl_b32 s2, s2, 13
	v_and_b32_e32 v14, 32, v14
	v_bitop3_b32 v19, v15, s2, v14 bitop3:0xde
	s_lshl_b32 s2, s13, 5
	s_add_i32 s44, s12, 0x18000
	s_and_b32 s2, s2, 0x60
	s_add_i32 s45, s44, s11
	s_lshl_b32 s13, s2, 7
	v_lshl_add_u64 v[6:7], v[6:7], 0, s[76:77]
	s_mov_b32 m0, s45
	s_add_i32 s48, s45, 0x2000
	s_add_i32 s49, s40, 0x8000
	s_add_i32 s50, s40, 0xa000
	s_waitcnt vmcnt(2)
	s_barrier
	global_load_lds_dwordx4 v[6:7], off
	v_lshl_add_u64 v[4:5], v[4:5], 0, s[76:77]
	s_mov_b32 m0, s48
	s_add_u32 s14, s22, 0x40080
	global_load_lds_dwordx4 v[4:5], off
	v_lshl_add_u64 v[0:1], v[0:1], 0, s[76:77]
	s_mov_b32 m0, s49
	s_addc_u32 s15, s23, 0
	s_add_i32 s51, s12, 0x1c000
	global_load_lds_dwordx4 v[0:1], off
	v_lshl_add_u64 v[0:1], v[2:3], 0, s[76:77]
	s_mov_b32 m0, s50
	s_add_i32 s60, s51, s11
	global_load_lds_dwordx4 v[0:1], off
	v_lshl_add_u64 v[0:1], s[14:15], 0, v[192:193]
	s_mov_b32 m0, s60
	s_add_i32 s61, s60, 0x2000
	global_load_lds_dwordx4 v[0:1], off
	v_lshl_add_u64 v[0:1], s[14:15], 0, v[128:129]
	s_mov_b32 m0, s61
	v_mov_b32_e32 v17, v193
	global_load_lds_dwordx4 v[0:1], off
	v_lshl_add_u64 v[0:1], s[4:5], 0, v[16:17]
	s_mov_b64 s[4:5], 0x3600000
	v_lshl_add_u64 v[134:135], v[0:1], 0, s[4:5]
	v_lshlrev_b32_e32 v0, 14, v8
	v_and_b32_e32 v0, 0xffff8000, v0
	v_lshl_add_u32 v0, v9, 11, v0
	v_and_b32_e32 v1, 1, v8
	v_lshl_or_b32 v0, v1, 6, v0
	v_lshl_add_u32 v136, v10, 1, v0
	v_lshlrev_b32_e32 v0, 14, v12
	v_and_b32_e32 v0, 0xffff8000, v0
	s_waitcnt vmcnt(6)
	v_lshl_add_u32 v0, v11, 11, v0
	v_and_b32_e32 v1, 1, v12
	s_cmpk_lt_u32 s10, 0x100
	v_lshl_or_b32 v0, v1, 6, v0
	v_bitop3_b32 v149, v15, s13, v14 bitop3:0xde
	s_cselect_b64 s[10:11], -1, 0
	s_ashr_i32 s64, s1, 31
	v_lshl_or_b32 v150, v18, 3, s2
	v_mov_b32_e32 v137, v193
	v_lshl_add_u32 v138, v13, 1, v0
	v_mov_b32_e32 v139, v193
	s_mov_b32 s65, 0
	v_add_u32_e32 v151, s12, v19
	s_barrier
	s_branch .LBB0_1218

; template <class Epi, class Sched, bool ALIGN_EPI = false, bool SP2 = false>
; __device__ __forceinline__ void gemm_phase(PG8_LAS unsigned char* lds, const Gemm g, const Sched& S, const Epi& E) {
;     ...
;     for (int i = 0; i < 2; ++i) { int R, C; stage_rc(tid * 16 + i * 8192, R, C); const int Rb = Epi::PERM ? ((R & ~31) + perm32(R & 31)) : R;
;         voffA[i] = (unsigned)(R * g.lda + C) * 2u; voffB[i] = (unsigned)(Rb * g.ldb + C) * 2u; }
;     const size_t kstep = (size_t)(BK * 2);
;     const size_t hstepA = (size_t)HALF * g.lda * 2, hstepB = (size_t)HALF * g.ldb * 2;
; __global__ void __launch_bounds__(NTHREADS, 2) mega_fwd(Args args) {
;     ...
;         {   PHASE_PTRS
;             pg8::Gemm g{ACT, (const bf16*)(ws + WS_W2B), M, DM, FFH, FFH, FFH}; pg8::StaticOrder S; S.init(M, DM, G_, bx_);
;             EpiRes E{XB, SSQ, 0.5f};
;             pg8::gemm_phase<EpiRes, pg8::StaticOrder, true, true>(ldsp, g, S, E);
.LBB0_1302:
	s_andn2_b64 vcc, exec, s[6:7]
	s_cbranch_vccnz .LBB0_1342
	v_ashrrev_i32_e32 v1, 31, v12
	v_lshrrev_b32_e32 v1, 26, v1
	v_add_u32_e32 v1, v12, v1
	v_ashrrev_i32_e32 v8, 6, v1
	v_bfe_i32 v1, v12, 27, 1
	v_lshlrev_b32_e32 v0, 4, v12
	v_lshrrev_b32_e32 v1, 22, v1
	v_add_u32_e32 v1, v0, v1
	v_and_b32_e32 v1, 0xfffffc00, v1
	v_sub_u32_e32 v1, v0, v1
	v_lshrrev_b32_e32 v2, 4, v1
	v_bitop3_b32 v1, v2, v1, 32 bitop3:0x6c
	v_ashrrev_i32_e32 v3, 31, v1
	v_lshrrev_b32_e32 v3, 26, v3
	v_lshlrev_b32_e32 v2, 3, v8
	v_add_u32_e32 v3, v1, v3
	v_and_b32_e32 v2, -16, v2
	v_ashrrev_i32_e32 v10, 6, v3
	v_and_b32_e32 v3, 0xc0, v3
	v_add_u32_e32 v2, v10, v2
	v_lshlrev_b32_e32 v4, 5, v8
	v_sub_u32_e32 v1, v1, v3
	v_and_b32_e32 v9, 32, v4
	v_ashrrev_i16_sdwa v1, v244, sext(v1) dst_sel:DWORD dst_unused:UNUSED_PAD src0_sel:DWORD src1_sel:BYTE_0
	v_lshlrev_b32_e32 v3, 1, v2
	v_lshrrev_b32_e32 v4, 2, v2
	v_and_b32_e32 v5, 3, v10
	s_mov_b32 s7, 0xffffe0
	v_bfe_i32 v11, v1, 0, 16
	v_and_b32_e32 v3, 24, v3
	v_and_b32_e32 v4, 4, v4
	v_and_or_b32 v5, v2, s7, v5
	s_movk_i32 s2, 0xb00
	v_add_u32_e32 v1, v9, v11
	v_or3_b32 v3, v5, v4, v3
	v_mul_lo_u32 v2, v2, s2
	v_add_lshl_u32 v128, v1, v2, 1
	v_mul_u32_u24_e32 v2, 0xb00, v3
	v_add_u32_e32 v0, 0x2000, v0
	v_add_lshl_u32 v192, v2, v1, 1
	v_ashrrev_i32_e32 v1, 31, v0
	v_lshrrev_b32_e32 v1, 22, v1
	v_add_u32_e32 v1, v0, v1
	v_ashrrev_i32_e32 v13, 10, v1
	v_mul_i32_i24_e32 v1, 0x400, v13
	v_sub_u32_e32 v0, v0, v1
	v_lshrrev_b32_e32 v1, 4, v0
	v_bitop3_b32 v0, v1, v0, 32 bitop3:0x6c
	v_ashrrev_i32_e32 v2, 31, v0
	s_add_u32 s28, s4, 0x7a00000
	v_lshrrev_b32_e32 v2, 26, v2
	s_addc_u32 s29, s5, 0
	v_lshlrev_b32_e32 v1, 3, v13
	v_add_u32_e32 v2, v0, v2
	s_add_u32 s30, s4, 0x2d00000
	v_and_b32_e32 v1, -16, v1
	v_ashrrev_i32_e32 v15, 6, v2
	s_addc_u32 s31, s5, 0
	s_ashr_i32 s6, s16, 6
	v_add_u32_e32 v1, v15, v1
	v_lshlrev_b32_e32 v3, 5, v13
	v_and_b32_e32 v2, 0xc0, v2
	v_and_b32_e32 v4, 3, v15
	v_and_b32_e32 v14, 32, v3
	v_sub_u32_e32 v0, v0, v2
	v_lshlrev_b32_e32 v2, 1, v1
	v_lshrrev_b32_e32 v3, 2, v1
	v_and_or_b32 v4, v1, s7, v4
	v_mul_lo_u32 v1, v1, s2
	s_ashr_i32 s7, s16, 8
	s_lshl_b32 s2, s6, 10
	s_mul_i32 s9, s34, 0x160000
	s_mul_hi_i32 s8, s34, 0x160000
	s_add_u32 s22, s30, s9
	s_addc_u32 s23, s31, s8
	s_add_i32 s35, s18, 0x10000
	s_add_i32 s36, s35, s2
	s_add_i32 s37, s36, 0x2000
	v_ashrrev_i16_sdwa v0, v244, sext(v0) dst_sel:DWORD dst_unused:UNUSED_PAD src0_sel:DWORD src1_sel:BYTE_0
	s_add_u32 s8, s22, 0xb0000
	v_bfe_i32 v16, v0, 0, 16
	v_and_b32_e32 v2, 24, v2
	v_and_b32_e32 v3, 4, v3
	s_addc_u32 s9, s23, 0
	s_add_i32 s38, s18, 0x14000
	v_add_u32_e32 v0, v14, v16
	v_or3_b32 v2, v4, v3, v2
	s_add_i32 s39, s38, s2
	v_add_lshl_u32 v130, v0, v1, 1
	v_mul_u32_u24_e32 v1, 0xb00, v2
	s_mul_i32 s11, s68, 0x160000
	s_mov_b32 m0, s36
	s_add_i32 s40, s39, 0x2000
	v_add_lshl_u32 v132, v1, v0, 1
	s_mul_hi_i32 s10, s68, 0x160000
	global_load_lds_dwordx4 v192, s[22:23]
	s_mov_b32 m0, s37
	s_add_u32 s20, s28, s11
	global_load_lds_dwordx4 v132, s[22:23]
	s_mov_b32 m0, s39
	s_addc_u32 s21, s29, s10
	s_add_i32 s41, s18, s2
	global_load_lds_dwordx4 v192, s[8:9]
	s_mov_b32 m0, s40
	s_add_i32 s42, s41, 0x2000
	global_load_lds_dwordx4 v132, s[8:9]
	s_mov_b32 m0, s41
	s_add_u32 s8, s20, 0xb0000
	global_load_lds_dwordx4 v128, s[20:21]
	s_mov_b32 m0, s42
	s_addc_u32 s9, s21, 0
	s_add_i32 s43, s41, 0x4000
	global_load_lds_dwordx4 v130, s[20:21]
	s_mov_b32 m0, s43
	s_add_i32 s44, s41, 0x6000
	global_load_lds_dwordx4 v128, s[8:9]
	s_mov_b32 m0, s44
	v_mov_b32_e32 v133, v193
	global_load_lds_dwordx4 v130, s[8:9]
	v_mov_b32_e32 v129, v193
	v_mov_b32_e32 v131, v193
	s_cmp_eq_u32 s7, 1
	v_lshl_add_u64 v[6:7], s[22:23], 0, v[192:193]
	v_lshl_add_u64 v[4:5], s[22:23], 0, v[132:133]
	v_lshl_add_u64 v[0:1], s[20:21], 0, v[128:129]
	s_cselect_b64 s[10:11], -1, 0
	s_cmp_lg_u32 s7, 1
	v_lshl_add_u64 v[2:3], s[20:21], 0, v[130:131]
	s_cbranch_scc1 .LBB0_1305
	s_barrier
